# up-GEMM K-loops: two of the four B-tile LDS-DMA loads of each SP2 load segment deferred into the following MFMA block (vmcnt 6 at the segment end)
# baseline (speedup 1.0000x reference)
.LBB0_1084:
	ds_read_b128 v[140:143], v150
	ds_read_b128 v[144:147], v150 offset:1024
	ds_read_b128 v[156:159], v150 offset:2048
	ds_read_b128 v[160:163], v150 offset:3072
	ds_read_b128 v[164:167], v151
	ds_read_b128 v[168:171], v151 offset:1024
	ds_read_b128 v[172:175], v151 offset:2048
	ds_read_b128 v[176:179], v151 offset:3072
	s_add_u32 s36, s0, 0xfff80080
	s_addc_u32 s37, s1, -1
	s_cmp_eq_u32 s74, 28
	s_cselect_b32 s39, s68, s37
	s_cselect_b32 s38, s69, s36
	s_cselect_b32 s37, s70, s73
	s_cselect_b32 s36, s71, s72
	s_sub_u32 s98, s0, 0x80000
	s_subb_u32 s99, s1, 0
	s_add_i32 m0, s85, 0x8000
	ds_read_b128 v[180:183], v152
	ds_read_b128 v[184:187], v152 offset:1024
	ds_read_b128 v[188:191], v152 offset:2048
	ds_read_b128 v[192:195], v152 offset:3072
	ds_read_b128 v[196:199], v152 offset:4096
	ds_read_b128 v[200:203], v152 offset:5120
	ds_read_b128 v[204:207], v152 offset:6144
	ds_read_b128 v[208:211], v152 offset:7168
	global_load_lds_dwordx4 v222, s[98:99]
	s_add_u32 s98, s98, 0x20000
	s_addc_u32 s99, s99, 0
	s_add_i32 m0, s85, 0x9000
	s_nop 0
	global_load_lds_dwordx4 v222, s[98:99]
	s_add_u32 s98, s98, 0x20000
	s_addc_u32 s99, s99, 0
	s_add_i32 m0, s85, 0xa000
	s_nop 0
	global_load_lds_dwordx4 v222, s[98:99]
	s_add_u32 s98, s98, 0x20000
	s_addc_u32 s99, s99, 0
	s_add_i32 m0, s85, 0xb000
	s_nop 0
	global_load_lds_dwordx4 v222, s[98:99]
	s_waitcnt vmcnt(8)
	s_waitcnt lgkmcnt(0)
	s_barrier
	s_setprio 1
	s_waitcnt lgkmcnt(0)
	v_mfma_f32_16x16x32_bf16 v[124:127], v[140:143], v[180:183], v[124:127]
	v_mfma_f32_16x16x32_bf16 v[120:123], v[156:159], v[180:183], v[120:123]
	v_mfma_f32_16x16x32_bf16 v[108:111], v[140:143], v[188:191], v[108:111]
	v_mfma_f32_16x16x32_bf16 v[104:107], v[156:159], v[188:191], v[104:107]
	v_mfma_f32_16x16x32_bf16 v[92:95], v[140:143], v[196:199], v[92:95]
	v_mfma_f32_16x16x32_bf16 v[88:91], v[156:159], v[196:199], v[88:91]
	v_mfma_f32_16x16x32_bf16 v[76:79], v[140:143], v[204:207], v[76:79]
	v_mfma_f32_16x16x32_bf16 v[72:75], v[156:159], v[204:207], v[72:75]
	v_mfma_f32_16x16x32_bf16 v[124:127], v[144:147], v[184:187], v[124:127]
	v_mfma_f32_16x16x32_bf16 v[120:123], v[160:163], v[184:187], v[120:123]
	v_mfma_f32_16x16x32_bf16 v[108:111], v[144:147], v[192:195], v[108:111]
	v_mfma_f32_16x16x32_bf16 v[104:107], v[160:163], v[192:195], v[104:107]
	v_mfma_f32_16x16x32_bf16 v[92:95], v[144:147], v[200:203], v[92:95]
	v_mfma_f32_16x16x32_bf16 v[88:91], v[160:163], v[200:203], v[88:91]
	v_mfma_f32_16x16x32_bf16 v[76:79], v[144:147], v[208:211], v[76:79]
	v_mfma_f32_16x16x32_bf16 v[72:75], v[160:163], v[208:211], v[72:75]
	s_setprio 0
	s_setprio 1
	v_mfma_f32_16x16x32_bf16 v[116:119], v[164:167], v[180:183], v[116:119]
	v_mfma_f32_16x16x32_bf16 v[112:115], v[172:175], v[180:183], v[112:115]
	v_mfma_f32_16x16x32_bf16 v[100:103], v[164:167], v[188:191], v[100:103]
	v_mfma_f32_16x16x32_bf16 v[96:99], v[172:175], v[188:191], v[96:99]
	v_mfma_f32_16x16x32_bf16 v[84:87], v[164:167], v[196:199], v[84:87]
	v_mfma_f32_16x16x32_bf16 v[80:83], v[172:175], v[196:199], v[80:83]
	v_mfma_f32_16x16x32_bf16 v[68:71], v[164:167], v[204:207], v[68:71]
	v_mfma_f32_16x16x32_bf16 v[64:67], v[172:175], v[204:207], v[64:67]
	v_mfma_f32_16x16x32_bf16 v[116:119], v[168:171], v[184:187], v[116:119]
	v_mfma_f32_16x16x32_bf16 v[112:115], v[176:179], v[184:187], v[112:115]
	v_mfma_f32_16x16x32_bf16 v[100:103], v[168:171], v[192:195], v[100:103]
	v_mfma_f32_16x16x32_bf16 v[96:99], v[176:179], v[192:195], v[96:99]
	v_mfma_f32_16x16x32_bf16 v[84:87], v[168:171], v[200:203], v[84:87]
	v_mfma_f32_16x16x32_bf16 v[80:83], v[176:179], v[200:203], v[80:83]
	v_mfma_f32_16x16x32_bf16 v[68:71], v[168:171], v[208:211], v[68:71]
	v_mfma_f32_16x16x32_bf16 v[64:67], v[176:179], v[208:211], v[64:67]
	s_setprio 0
	s_barrier
	s_add_i32 s75, s56, s5
	v_lshl_add_u64 v[212:213], s[36:37], 0, v[130:131]
	s_mov_b32 m0, s75
	ds_read_b128 v[180:183], v152 offset:16384
	ds_read_b128 v[184:187], v152 offset:17408
	ds_read_b128 v[188:191], v152 offset:18432
	ds_read_b128 v[192:195], v152 offset:19456
	ds_read_b128 v[196:199], v152 offset:20480
	ds_read_b128 v[200:203], v152 offset:21504
	ds_read_b128 v[204:207], v152 offset:22528
	ds_read_b128 v[208:211], v152 offset:23552
	global_load_lds_dwordx4 v[212:213], off
	s_add_i32 m0, s75, 0x2000
	s_add_u32 s76, s36, 0x80000
	v_lshl_add_u64 v[214:215], s[36:37], 0, v[134:135]
	s_addc_u32 s77, s37, 0
	s_add_i32 s75, s57, s5
	global_load_lds_dwordx4 v[214:215], off
	v_lshl_add_u64 v[216:217], s[76:77], 0, v[130:131]
	v_lshl_add_u64 v[224:225], s[76:77], 0, v[134:135]
	s_waitcnt vmcnt(6)
	s_waitcnt lgkmcnt(0)
	s_barrier
	s_setprio 1
	s_waitcnt lgkmcnt(0)
	v_mfma_f32_16x16x32_bf16 v[60:63], v[140:143], v[180:183], v[60:63]
	v_mfma_f32_16x16x32_bf16 v[56:59], v[156:159], v[180:183], v[56:59]
	v_mfma_f32_16x16x32_bf16 v[44:47], v[140:143], v[188:191], v[44:47]
	v_mfma_f32_16x16x32_bf16 v[40:43], v[156:159], v[188:191], v[40:43]
	v_mfma_f32_16x16x32_bf16 v[28:31], v[140:143], v[196:199], v[28:31]
	v_mfma_f32_16x16x32_bf16 v[24:27], v[156:159], v[196:199], v[24:27]
	v_mfma_f32_16x16x32_bf16 v[12:15], v[140:143], v[204:207], v[12:15]
	v_mfma_f32_16x16x32_bf16 v[8:11], v[156:159], v[204:207], v[8:11]
	s_mov_b32 m0, s75
	s_nop 0
	global_load_lds_dwordx4 v[216:217], off
	v_mfma_f32_16x16x32_bf16 v[60:63], v[144:147], v[184:187], v[60:63]
	v_mfma_f32_16x16x32_bf16 v[56:59], v[160:163], v[184:187], v[56:59]
	v_mfma_f32_16x16x32_bf16 v[44:47], v[144:147], v[192:195], v[44:47]
	v_mfma_f32_16x16x32_bf16 v[40:43], v[160:163], v[192:195], v[40:43]
	v_mfma_f32_16x16x32_bf16 v[28:31], v[144:147], v[200:203], v[28:31]
	v_mfma_f32_16x16x32_bf16 v[24:27], v[160:163], v[200:203], v[24:27]
	v_mfma_f32_16x16x32_bf16 v[12:15], v[144:147], v[208:211], v[12:15]
	v_mfma_f32_16x16x32_bf16 v[8:11], v[160:163], v[208:211], v[8:11]
	s_setprio 0
	s_setprio 1
	v_mfma_f32_16x16x32_bf16 v[52:55], v[164:167], v[180:183], v[52:55]
	v_mfma_f32_16x16x32_bf16 v[48:51], v[172:175], v[180:183], v[48:51]
	v_mfma_f32_16x16x32_bf16 v[36:39], v[164:167], v[188:191], v[36:39]
	v_mfma_f32_16x16x32_bf16 v[32:35], v[172:175], v[188:191], v[32:35]
	v_mfma_f32_16x16x32_bf16 v[20:23], v[164:167], v[196:199], v[20:23]
	v_mfma_f32_16x16x32_bf16 v[16:19], v[172:175], v[196:199], v[16:19]
	v_mfma_f32_16x16x32_bf16 v[4:7], v[164:167], v[204:207], v[4:7]
	v_mfma_f32_16x16x32_bf16 v[0:3], v[172:175], v[204:207], v[0:3]
	s_add_i32 m0, s75, 0x2000
	s_nop 0
	global_load_lds_dwordx4 v[224:225], off
	v_mfma_f32_16x16x32_bf16 v[52:55], v[168:171], v[184:187], v[52:55]
	v_mfma_f32_16x16x32_bf16 v[48:51], v[176:179], v[184:187], v[48:51]
	v_mfma_f32_16x16x32_bf16 v[36:39], v[168:171], v[192:195], v[36:39]
	v_mfma_f32_16x16x32_bf16 v[32:35], v[176:179], v[192:195], v[32:35]
	v_mfma_f32_16x16x32_bf16 v[20:23], v[168:171], v[200:203], v[20:23]
	v_mfma_f32_16x16x32_bf16 v[16:19], v[176:179], v[200:203], v[16:19]
	v_mfma_f32_16x16x32_bf16 v[4:7], v[168:171], v[208:211], v[4:7]
	v_mfma_f32_16x16x32_bf16 v[0:3], v[176:179], v[208:211], v[0:3]
	s_setprio 0
	s_waitcnt vmcnt(4)
	s_barrier
	ds_read_b128 v[140:143], v153
	ds_read_b128 v[144:147], v153 offset:1024
	ds_read_b128 v[156:159], v153 offset:2048
	ds_read_b128 v[160:163], v153 offset:3072
	ds_read_b128 v[164:167], v154
	ds_read_b128 v[168:171], v154 offset:1024
	ds_read_b128 v[172:175], v154 offset:2048
	ds_read_b128 v[176:179], v154 offset:3072
	s_mov_b32 s98, s38
	s_mov_b32 s99, s39
	s_add_i32 m0, s85, 0
	ds_read_b128 v[180:183], v152 offset:32768
	ds_read_b128 v[184:187], v152 offset:33792
	ds_read_b128 v[188:191], v152 offset:34816
	ds_read_b128 v[192:195], v152 offset:35840
	ds_read_b128 v[196:199], v152 offset:36864
	ds_read_b128 v[200:203], v152 offset:37888
	ds_read_b128 v[204:207], v152 offset:38912
	ds_read_b128 v[208:211], v152 offset:39936
	global_load_lds_dwordx4 v222, s[98:99]
	s_add_u32 s98, s98, 0x20000
	s_addc_u32 s99, s99, 0
	s_add_i32 m0, s85, 0x1000
	s_nop 0
	global_load_lds_dwordx4 v222, s[98:99]
	s_add_u32 s98, s98, 0x20000
	s_addc_u32 s99, s99, 0
	s_add_i32 m0, s85, 0x2000
	s_nop 0
	global_load_lds_dwordx4 v222, s[98:99]
	s_add_u32 s98, s98, 0x20000
	s_addc_u32 s99, s99, 0
	s_add_i32 m0, s85, 0x3000
	s_nop 0
	global_load_lds_dwordx4 v222, s[98:99]
	s_waitcnt vmcnt(8)
	s_waitcnt lgkmcnt(0)
	s_barrier
	s_setprio 1
	s_waitcnt lgkmcnt(0)
	v_mfma_f32_16x16x32_bf16 v[124:127], v[140:143], v[180:183], v[124:127]
	v_mfma_f32_16x16x32_bf16 v[120:123], v[156:159], v[180:183], v[120:123]
	v_mfma_f32_16x16x32_bf16 v[108:111], v[140:143], v[188:191], v[108:111]
	v_mfma_f32_16x16x32_bf16 v[104:107], v[156:159], v[188:191], v[104:107]
	v_mfma_f32_16x16x32_bf16 v[92:95], v[140:143], v[196:199], v[92:95]
	v_mfma_f32_16x16x32_bf16 v[88:91], v[156:159], v[196:199], v[88:91]
	v_mfma_f32_16x16x32_bf16 v[76:79], v[140:143], v[204:207], v[76:79]
	v_mfma_f32_16x16x32_bf16 v[72:75], v[156:159], v[204:207], v[72:75]
	v_mfma_f32_16x16x32_bf16 v[124:127], v[144:147], v[184:187], v[124:127]
	v_mfma_f32_16x16x32_bf16 v[120:123], v[160:163], v[184:187], v[120:123]
	v_mfma_f32_16x16x32_bf16 v[108:111], v[144:147], v[192:195], v[108:111]
	v_mfma_f32_16x16x32_bf16 v[104:107], v[160:163], v[192:195], v[104:107]
	v_mfma_f32_16x16x32_bf16 v[92:95], v[144:147], v[200:203], v[92:95]
	v_mfma_f32_16x16x32_bf16 v[88:91], v[160:163], v[200:203], v[88:91]
	v_mfma_f32_16x16x32_bf16 v[76:79], v[144:147], v[208:211], v[76:79]
	v_mfma_f32_16x16x32_bf16 v[72:75], v[160:163], v[208:211], v[72:75]
	s_setprio 0
	s_setprio 1
	v_mfma_f32_16x16x32_bf16 v[116:119], v[164:167], v[180:183], v[116:119]
	v_mfma_f32_16x16x32_bf16 v[112:115], v[172:175], v[180:183], v[112:115]
	v_mfma_f32_16x16x32_bf16 v[100:103], v[164:167], v[188:191], v[100:103]
	v_mfma_f32_16x16x32_bf16 v[96:99], v[172:175], v[188:191], v[96:99]
	v_mfma_f32_16x16x32_bf16 v[84:87], v[164:167], v[196:199], v[84:87]
	v_mfma_f32_16x16x32_bf16 v[80:83], v[172:175], v[196:199], v[80:83]
	v_mfma_f32_16x16x32_bf16 v[68:71], v[164:167], v[204:207], v[68:71]
	v_mfma_f32_16x16x32_bf16 v[64:67], v[172:175], v[204:207], v[64:67]
	v_mfma_f32_16x16x32_bf16 v[116:119], v[168:171], v[184:187], v[116:119]
	v_mfma_f32_16x16x32_bf16 v[112:115], v[176:179], v[184:187], v[112:115]
	v_mfma_f32_16x16x32_bf16 v[100:103], v[168:171], v[192:195], v[100:103]
	v_mfma_f32_16x16x32_bf16 v[96:99], v[176:179], v[192:195], v[96:99]
	v_mfma_f32_16x16x32_bf16 v[84:87], v[168:171], v[200:203], v[84:87]
	v_mfma_f32_16x16x32_bf16 v[80:83], v[176:179], v[200:203], v[80:83]
	v_mfma_f32_16x16x32_bf16 v[68:71], v[168:171], v[208:211], v[68:71]
	v_mfma_f32_16x16x32_bf16 v[64:67], v[176:179], v[208:211], v[64:67]
	s_setprio 0
	s_barrier
	s_add_i32 s38, s58, s5
	v_lshl_add_u64 v[212:213], v[212:213], 0, s[14:15]
	s_mov_b32 m0, s38
	ds_read_b128 v[180:183], v152 offset:49152
	ds_read_b128 v[184:187], v152 offset:50176
	ds_read_b128 v[188:191], v152 offset:51200
	ds_read_b128 v[192:195], v152 offset:52224
	ds_read_b128 v[196:199], v152 offset:53248
	ds_read_b128 v[200:203], v152 offset:54272
	ds_read_b128 v[204:207], v152 offset:55296
	ds_read_b128 v[208:211], v152 offset:56320
	global_load_lds_dwordx4 v[212:213], off
	s_add_i32 m0, s38, 0x2000
	s_add_u32 s36, s36, 0x80080
	v_lshl_add_u64 v[212:213], v[214:215], 0, s[14:15]
	s_addc_u32 s37, s37, 0
	s_add_i32 s38, s59, s5
	global_load_lds_dwordx4 v[212:213], off
	v_lshl_add_u64 v[226:227], s[36:37], 0, v[130:131]
	v_lshl_add_u64 v[228:229], s[36:37], 0, v[134:135]
	s_waitcnt vmcnt(6)
	s_waitcnt lgkmcnt(0)
	s_barrier
	s_setprio 1
	s_waitcnt lgkmcnt(0)
	v_mfma_f32_16x16x32_bf16 v[60:63], v[140:143], v[180:183], v[60:63]
	v_mfma_f32_16x16x32_bf16 v[56:59], v[156:159], v[180:183], v[56:59]
	v_mfma_f32_16x16x32_bf16 v[44:47], v[140:143], v[188:191], v[44:47]
	v_mfma_f32_16x16x32_bf16 v[40:43], v[156:159], v[188:191], v[40:43]
	v_mfma_f32_16x16x32_bf16 v[28:31], v[140:143], v[196:199], v[28:31]
	v_mfma_f32_16x16x32_bf16 v[24:27], v[156:159], v[196:199], v[24:27]
	v_mfma_f32_16x16x32_bf16 v[12:15], v[140:143], v[204:207], v[12:15]
	v_mfma_f32_16x16x32_bf16 v[8:11], v[156:159], v[204:207], v[8:11]
	s_mov_b32 m0, s38
	s_nop 0
	global_load_lds_dwordx4 v[226:227], off
	v_mfma_f32_16x16x32_bf16 v[60:63], v[144:147], v[184:187], v[60:63]
	v_mfma_f32_16x16x32_bf16 v[56:59], v[160:163], v[184:187], v[56:59]
	v_mfma_f32_16x16x32_bf16 v[44:47], v[144:147], v[192:195], v[44:47]
	v_mfma_f32_16x16x32_bf16 v[40:43], v[160:163], v[192:195], v[40:43]
	v_mfma_f32_16x16x32_bf16 v[28:31], v[144:147], v[200:203], v[28:31]
	v_mfma_f32_16x16x32_bf16 v[24:27], v[160:163], v[200:203], v[24:27]
	v_mfma_f32_16x16x32_bf16 v[12:15], v[144:147], v[208:211], v[12:15]
	v_mfma_f32_16x16x32_bf16 v[8:11], v[160:163], v[208:211], v[8:11]
	s_setprio 0
	s_setprio 1
	v_mfma_f32_16x16x32_bf16 v[52:55], v[164:167], v[180:183], v[52:55]
	v_mfma_f32_16x16x32_bf16 v[48:51], v[172:175], v[180:183], v[48:51]
	v_mfma_f32_16x16x32_bf16 v[36:39], v[164:167], v[188:191], v[36:39]
	v_mfma_f32_16x16x32_bf16 v[32:35], v[172:175], v[188:191], v[32:35]
	v_mfma_f32_16x16x32_bf16 v[20:23], v[164:167], v[196:199], v[20:23]
	v_mfma_f32_16x16x32_bf16 v[16:19], v[172:175], v[196:199], v[16:19]
	v_mfma_f32_16x16x32_bf16 v[4:7], v[164:167], v[204:207], v[4:7]
	v_mfma_f32_16x16x32_bf16 v[0:3], v[172:175], v[204:207], v[0:3]
	s_add_i32 m0, s38, 0x2000
	s_nop 0
	global_load_lds_dwordx4 v[228:229], off
	v_mfma_f32_16x16x32_bf16 v[52:55], v[168:171], v[184:187], v[52:55]
	v_mfma_f32_16x16x32_bf16 v[48:51], v[176:179], v[184:187], v[48:51]
	v_mfma_f32_16x16x32_bf16 v[36:39], v[168:171], v[192:195], v[36:39]
	v_mfma_f32_16x16x32_bf16 v[32:35], v[176:179], v[192:195], v[32:35]
	v_mfma_f32_16x16x32_bf16 v[20:23], v[168:171], v[200:203], v[20:23]
	v_mfma_f32_16x16x32_bf16 v[16:19], v[176:179], v[200:203], v[16:19]
	v_mfma_f32_16x16x32_bf16 v[4:7], v[168:171], v[208:211], v[4:7]
	v_mfma_f32_16x16x32_bf16 v[0:3], v[176:179], v[208:211], v[0:3]
	s_setprio 0
	s_waitcnt vmcnt(4)
	s_barrier
	s_add_i32 s74, s74, 2
	s_add_u32 s0, s0, 0x100
	s_addc_u32 s1, s1, 0
	s_add_u32 s72, s72, 0x100
	s_addc_u32 s73, s73, 0
	s_cmp_gt_u32 s74, 29
	s_cbranch_scc0 .LBB0_1084
	s_and_b64 vcc, exec, s[16:17]
	s_cbranch_vccz .LBB0_1087
	s_barrier

.LBB0_1955:
	ds_read_b128 v[140:143], v150
	ds_read_b128 v[144:147], v150 offset:1024
	ds_read_b128 v[156:159], v150 offset:2048
	ds_read_b128 v[160:163], v150 offset:3072
	ds_read_b128 v[164:167], v151
	ds_read_b128 v[168:171], v151 offset:1024
	ds_read_b128 v[172:175], v151 offset:2048
	ds_read_b128 v[176:179], v151 offset:3072
	s_add_u32 s36, s0, 0xfff80080
	s_addc_u32 s37, s1, -1
	s_cmp_eq_u32 s74, 28
	s_cselect_b32 s39, s68, s37
	s_cselect_b32 s38, s69, s36
	s_cselect_b32 s37, s70, s73
	s_cselect_b32 s36, s71, s72
	s_sub_u32 s98, s0, 0x80000
	s_subb_u32 s99, s1, 0
	s_add_i32 m0, s85, 0x8000
	ds_read_b128 v[180:183], v152
	ds_read_b128 v[184:187], v152 offset:1024
	ds_read_b128 v[188:191], v152 offset:2048
	ds_read_b128 v[192:195], v152 offset:3072
	ds_read_b128 v[196:199], v152 offset:4096
	ds_read_b128 v[200:203], v152 offset:5120
	ds_read_b128 v[204:207], v152 offset:6144
	ds_read_b128 v[208:211], v152 offset:7168
	global_load_lds_dwordx4 v222, s[98:99]
	s_add_u32 s98, s98, 0x20000
	s_addc_u32 s99, s99, 0
	s_add_i32 m0, s85, 0x9000
	s_nop 0
	global_load_lds_dwordx4 v222, s[98:99]
	s_add_u32 s98, s98, 0x20000
	s_addc_u32 s99, s99, 0
	s_add_i32 m0, s85, 0xa000
	s_nop 0
	global_load_lds_dwordx4 v222, s[98:99]
	s_add_u32 s98, s98, 0x20000
	s_addc_u32 s99, s99, 0
	s_add_i32 m0, s85, 0xb000
	s_nop 0
	global_load_lds_dwordx4 v222, s[98:99]
	s_waitcnt vmcnt(8)
	s_waitcnt lgkmcnt(0)
	s_barrier
	s_setprio 1
	s_waitcnt lgkmcnt(0)
	v_mfma_f32_16x16x32_bf16 v[124:127], v[140:143], v[180:183], v[124:127]
	v_mfma_f32_16x16x32_bf16 v[120:123], v[156:159], v[180:183], v[120:123]
	v_mfma_f32_16x16x32_bf16 v[108:111], v[140:143], v[188:191], v[108:111]
	v_mfma_f32_16x16x32_bf16 v[104:107], v[156:159], v[188:191], v[104:107]
	v_mfma_f32_16x16x32_bf16 v[92:95], v[140:143], v[196:199], v[92:95]
	v_mfma_f32_16x16x32_bf16 v[88:91], v[156:159], v[196:199], v[88:91]
	v_mfma_f32_16x16x32_bf16 v[76:79], v[140:143], v[204:207], v[76:79]
	v_mfma_f32_16x16x32_bf16 v[72:75], v[156:159], v[204:207], v[72:75]
	v_mfma_f32_16x16x32_bf16 v[124:127], v[144:147], v[184:187], v[124:127]
	v_mfma_f32_16x16x32_bf16 v[120:123], v[160:163], v[184:187], v[120:123]
	v_mfma_f32_16x16x32_bf16 v[108:111], v[144:147], v[192:195], v[108:111]
	v_mfma_f32_16x16x32_bf16 v[104:107], v[160:163], v[192:195], v[104:107]
	v_mfma_f32_16x16x32_bf16 v[92:95], v[144:147], v[200:203], v[92:95]
	v_mfma_f32_16x16x32_bf16 v[88:91], v[160:163], v[200:203], v[88:91]
	v_mfma_f32_16x16x32_bf16 v[76:79], v[144:147], v[208:211], v[76:79]
	v_mfma_f32_16x16x32_bf16 v[72:75], v[160:163], v[208:211], v[72:75]
	s_setprio 0
	s_setprio 1
	v_mfma_f32_16x16x32_bf16 v[116:119], v[164:167], v[180:183], v[116:119]
	v_mfma_f32_16x16x32_bf16 v[112:115], v[172:175], v[180:183], v[112:115]
	v_mfma_f32_16x16x32_bf16 v[100:103], v[164:167], v[188:191], v[100:103]
	v_mfma_f32_16x16x32_bf16 v[96:99], v[172:175], v[188:191], v[96:99]
	v_mfma_f32_16x16x32_bf16 v[84:87], v[164:167], v[196:199], v[84:87]
	v_mfma_f32_16x16x32_bf16 v[80:83], v[172:175], v[196:199], v[80:83]
	v_mfma_f32_16x16x32_bf16 v[68:71], v[164:167], v[204:207], v[68:71]
	v_mfma_f32_16x16x32_bf16 v[64:67], v[172:175], v[204:207], v[64:67]
	v_mfma_f32_16x16x32_bf16 v[116:119], v[168:171], v[184:187], v[116:119]
	v_mfma_f32_16x16x32_bf16 v[112:115], v[176:179], v[184:187], v[112:115]
	v_mfma_f32_16x16x32_bf16 v[100:103], v[168:171], v[192:195], v[100:103]
	v_mfma_f32_16x16x32_bf16 v[96:99], v[176:179], v[192:195], v[96:99]
	v_mfma_f32_16x16x32_bf16 v[84:87], v[168:171], v[200:203], v[84:87]
	v_mfma_f32_16x16x32_bf16 v[80:83], v[176:179], v[200:203], v[80:83]
	v_mfma_f32_16x16x32_bf16 v[68:71], v[168:171], v[208:211], v[68:71]
	v_mfma_f32_16x16x32_bf16 v[64:67], v[176:179], v[208:211], v[64:67]
	s_setprio 0
	s_barrier
	s_add_i32 s75, s56, s7
	v_lshl_add_u64 v[212:213], s[36:37], 0, v[130:131]
	s_mov_b32 m0, s75
	ds_read_b128 v[180:183], v152 offset:16384
	ds_read_b128 v[184:187], v152 offset:17408
	ds_read_b128 v[188:191], v152 offset:18432
	ds_read_b128 v[192:195], v152 offset:19456
	ds_read_b128 v[196:199], v152 offset:20480
	ds_read_b128 v[200:203], v152 offset:21504
	ds_read_b128 v[204:207], v152 offset:22528
	ds_read_b128 v[208:211], v152 offset:23552
	global_load_lds_dwordx4 v[212:213], off
	s_add_i32 m0, s75, 0x2000
	s_add_u32 s76, s36, 0x80000
	v_lshl_add_u64 v[214:215], s[36:37], 0, v[134:135]
	s_addc_u32 s77, s37, 0
	s_add_i32 s75, s57, s7
	global_load_lds_dwordx4 v[214:215], off
	v_lshl_add_u64 v[216:217], s[76:77], 0, v[130:131]
	v_lshl_add_u64 v[224:225], s[76:77], 0, v[134:135]
	s_waitcnt vmcnt(6)
	s_waitcnt lgkmcnt(0)
	s_barrier
	s_setprio 1
	s_waitcnt lgkmcnt(0)
	v_mfma_f32_16x16x32_bf16 v[60:63], v[140:143], v[180:183], v[60:63]
	v_mfma_f32_16x16x32_bf16 v[56:59], v[156:159], v[180:183], v[56:59]
	v_mfma_f32_16x16x32_bf16 v[44:47], v[140:143], v[188:191], v[44:47]
	v_mfma_f32_16x16x32_bf16 v[40:43], v[156:159], v[188:191], v[40:43]
	v_mfma_f32_16x16x32_bf16 v[28:31], v[140:143], v[196:199], v[28:31]
	v_mfma_f32_16x16x32_bf16 v[24:27], v[156:159], v[196:199], v[24:27]
	v_mfma_f32_16x16x32_bf16 v[12:15], v[140:143], v[204:207], v[12:15]
	v_mfma_f32_16x16x32_bf16 v[8:11], v[156:159], v[204:207], v[8:11]
	s_mov_b32 m0, s75
	s_nop 0
	global_load_lds_dwordx4 v[216:217], off
	v_mfma_f32_16x16x32_bf16 v[60:63], v[144:147], v[184:187], v[60:63]
	v_mfma_f32_16x16x32_bf16 v[56:59], v[160:163], v[184:187], v[56:59]
	v_mfma_f32_16x16x32_bf16 v[44:47], v[144:147], v[192:195], v[44:47]
	v_mfma_f32_16x16x32_bf16 v[40:43], v[160:163], v[192:195], v[40:43]
	v_mfma_f32_16x16x32_bf16 v[28:31], v[144:147], v[200:203], v[28:31]
	v_mfma_f32_16x16x32_bf16 v[24:27], v[160:163], v[200:203], v[24:27]
	v_mfma_f32_16x16x32_bf16 v[12:15], v[144:147], v[208:211], v[12:15]
	v_mfma_f32_16x16x32_bf16 v[8:11], v[160:163], v[208:211], v[8:11]
	s_setprio 0
	s_setprio 1
	v_mfma_f32_16x16x32_bf16 v[52:55], v[164:167], v[180:183], v[52:55]
	v_mfma_f32_16x16x32_bf16 v[48:51], v[172:175], v[180:183], v[48:51]
	v_mfma_f32_16x16x32_bf16 v[36:39], v[164:167], v[188:191], v[36:39]
	v_mfma_f32_16x16x32_bf16 v[32:35], v[172:175], v[188:191], v[32:35]
	v_mfma_f32_16x16x32_bf16 v[20:23], v[164:167], v[196:199], v[20:23]
	v_mfma_f32_16x16x32_bf16 v[16:19], v[172:175], v[196:199], v[16:19]
	v_mfma_f32_16x16x32_bf16 v[4:7], v[164:167], v[204:207], v[4:7]
	v_mfma_f32_16x16x32_bf16 v[0:3], v[172:175], v[204:207], v[0:3]
	s_add_i32 m0, s75, 0x2000
	s_nop 0
	global_load_lds_dwordx4 v[224:225], off
	v_mfma_f32_16x16x32_bf16 v[52:55], v[168:171], v[184:187], v[52:55]
	v_mfma_f32_16x16x32_bf16 v[48:51], v[176:179], v[184:187], v[48:51]
	v_mfma_f32_16x16x32_bf16 v[36:39], v[168:171], v[192:195], v[36:39]
	v_mfma_f32_16x16x32_bf16 v[32:35], v[176:179], v[192:195], v[32:35]
	v_mfma_f32_16x16x32_bf16 v[20:23], v[168:171], v[200:203], v[20:23]
	v_mfma_f32_16x16x32_bf16 v[16:19], v[176:179], v[200:203], v[16:19]
	v_mfma_f32_16x16x32_bf16 v[4:7], v[168:171], v[208:211], v[4:7]
	v_mfma_f32_16x16x32_bf16 v[0:3], v[176:179], v[208:211], v[0:3]
	s_setprio 0
	s_waitcnt vmcnt(4)
	s_barrier
	ds_read_b128 v[140:143], v153
	ds_read_b128 v[144:147], v153 offset:1024
	ds_read_b128 v[156:159], v153 offset:2048
	ds_read_b128 v[160:163], v153 offset:3072
	ds_read_b128 v[164:167], v154
	ds_read_b128 v[168:171], v154 offset:1024
	ds_read_b128 v[172:175], v154 offset:2048
	ds_read_b128 v[176:179], v154 offset:3072
	s_mov_b32 s98, s38
	s_mov_b32 s99, s39
	s_add_i32 m0, s85, 0
	ds_read_b128 v[180:183], v152 offset:32768
	ds_read_b128 v[184:187], v152 offset:33792
	ds_read_b128 v[188:191], v152 offset:34816
	ds_read_b128 v[192:195], v152 offset:35840
	ds_read_b128 v[196:199], v152 offset:36864
	ds_read_b128 v[200:203], v152 offset:37888
	ds_read_b128 v[204:207], v152 offset:38912
	ds_read_b128 v[208:211], v152 offset:39936
	global_load_lds_dwordx4 v222, s[98:99]
	s_add_u32 s98, s98, 0x20000
	s_addc_u32 s99, s99, 0
	s_add_i32 m0, s85, 0x1000
	s_nop 0
	global_load_lds_dwordx4 v222, s[98:99]
	s_add_u32 s98, s98, 0x20000
	s_addc_u32 s99, s99, 0
	s_add_i32 m0, s85, 0x2000
	s_nop 0
	global_load_lds_dwordx4 v222, s[98:99]
	s_add_u32 s98, s98, 0x20000
	s_addc_u32 s99, s99, 0
	s_add_i32 m0, s85, 0x3000
	s_nop 0
	global_load_lds_dwordx4 v222, s[98:99]
	s_waitcnt vmcnt(8)
	s_waitcnt lgkmcnt(0)
	s_barrier
	s_setprio 1
	s_waitcnt lgkmcnt(0)
	v_mfma_f32_16x16x32_bf16 v[124:127], v[140:143], v[180:183], v[124:127]
	v_mfma_f32_16x16x32_bf16 v[120:123], v[156:159], v[180:183], v[120:123]
	v_mfma_f32_16x16x32_bf16 v[108:111], v[140:143], v[188:191], v[108:111]
	v_mfma_f32_16x16x32_bf16 v[104:107], v[156:159], v[188:191], v[104:107]
	v_mfma_f32_16x16x32_bf16 v[92:95], v[140:143], v[196:199], v[92:95]
	v_mfma_f32_16x16x32_bf16 v[88:91], v[156:159], v[196:199], v[88:91]
	v_mfma_f32_16x16x32_bf16 v[76:79], v[140:143], v[204:207], v[76:79]
	v_mfma_f32_16x16x32_bf16 v[72:75], v[156:159], v[204:207], v[72:75]
	v_mfma_f32_16x16x32_bf16 v[124:127], v[144:147], v[184:187], v[124:127]
	v_mfma_f32_16x16x32_bf16 v[120:123], v[160:163], v[184:187], v[120:123]
	v_mfma_f32_16x16x32_bf16 v[108:111], v[144:147], v[192:195], v[108:111]
	v_mfma_f32_16x16x32_bf16 v[104:107], v[160:163], v[192:195], v[104:107]
	v_mfma_f32_16x16x32_bf16 v[92:95], v[144:147], v[200:203], v[92:95]
	v_mfma_f32_16x16x32_bf16 v[88:91], v[160:163], v[200:203], v[88:91]
	v_mfma_f32_16x16x32_bf16 v[76:79], v[144:147], v[208:211], v[76:79]
	v_mfma_f32_16x16x32_bf16 v[72:75], v[160:163], v[208:211], v[72:75]
	s_setprio 0
	s_setprio 1
	v_mfma_f32_16x16x32_bf16 v[116:119], v[164:167], v[180:183], v[116:119]
	v_mfma_f32_16x16x32_bf16 v[112:115], v[172:175], v[180:183], v[112:115]
	v_mfma_f32_16x16x32_bf16 v[100:103], v[164:167], v[188:191], v[100:103]
	v_mfma_f32_16x16x32_bf16 v[96:99], v[172:175], v[188:191], v[96:99]
	v_mfma_f32_16x16x32_bf16 v[84:87], v[164:167], v[196:199], v[84:87]
	v_mfma_f32_16x16x32_bf16 v[80:83], v[172:175], v[196:199], v[80:83]
	v_mfma_f32_16x16x32_bf16 v[68:71], v[164:167], v[204:207], v[68:71]
	v_mfma_f32_16x16x32_bf16 v[64:67], v[172:175], v[204:207], v[64:67]
	v_mfma_f32_16x16x32_bf16 v[116:119], v[168:171], v[184:187], v[116:119]
	v_mfma_f32_16x16x32_bf16 v[112:115], v[176:179], v[184:187], v[112:115]
	v_mfma_f32_16x16x32_bf16 v[100:103], v[168:171], v[192:195], v[100:103]
	v_mfma_f32_16x16x32_bf16 v[96:99], v[176:179], v[192:195], v[96:99]
	v_mfma_f32_16x16x32_bf16 v[84:87], v[168:171], v[200:203], v[84:87]
	v_mfma_f32_16x16x32_bf16 v[80:83], v[176:179], v[200:203], v[80:83]
	v_mfma_f32_16x16x32_bf16 v[68:71], v[168:171], v[208:211], v[68:71]
	v_mfma_f32_16x16x32_bf16 v[64:67], v[176:179], v[208:211], v[64:67]
	s_setprio 0
	s_barrier
	s_add_i32 s38, s58, s7
	v_lshl_add_u64 v[212:213], v[212:213], 0, s[14:15]
	s_mov_b32 m0, s38
	ds_read_b128 v[180:183], v152 offset:49152
	ds_read_b128 v[184:187], v152 offset:50176
	ds_read_b128 v[188:191], v152 offset:51200
	ds_read_b128 v[192:195], v152 offset:52224
	ds_read_b128 v[196:199], v152 offset:53248
	ds_read_b128 v[200:203], v152 offset:54272
	ds_read_b128 v[204:207], v152 offset:55296
	ds_read_b128 v[208:211], v152 offset:56320
	global_load_lds_dwordx4 v[212:213], off
	s_add_i32 m0, s38, 0x2000
	s_add_u32 s36, s36, 0x80080
	v_lshl_add_u64 v[212:213], v[214:215], 0, s[14:15]
	s_addc_u32 s37, s37, 0
	s_add_i32 s38, s59, s7
	global_load_lds_dwordx4 v[212:213], off
	v_lshl_add_u64 v[226:227], s[36:37], 0, v[130:131]
	v_lshl_add_u64 v[228:229], s[36:37], 0, v[134:135]
	s_waitcnt vmcnt(6)
	s_waitcnt lgkmcnt(0)
	s_barrier
	s_setprio 1
	s_waitcnt lgkmcnt(0)
	v_mfma_f32_16x16x32_bf16 v[60:63], v[140:143], v[180:183], v[60:63]
	v_mfma_f32_16x16x32_bf16 v[56:59], v[156:159], v[180:183], v[56:59]
	v_mfma_f32_16x16x32_bf16 v[44:47], v[140:143], v[188:191], v[44:47]
	v_mfma_f32_16x16x32_bf16 v[40:43], v[156:159], v[188:191], v[40:43]
	v_mfma_f32_16x16x32_bf16 v[28:31], v[140:143], v[196:199], v[28:31]
	v_mfma_f32_16x16x32_bf16 v[24:27], v[156:159], v[196:199], v[24:27]
	v_mfma_f32_16x16x32_bf16 v[12:15], v[140:143], v[204:207], v[12:15]
	v_mfma_f32_16x16x32_bf16 v[8:11], v[156:159], v[204:207], v[8:11]
	s_mov_b32 m0, s38
	s_nop 0
	global_load_lds_dwordx4 v[226:227], off
	v_mfma_f32_16x16x32_bf16 v[60:63], v[144:147], v[184:187], v[60:63]
	v_mfma_f32_16x16x32_bf16 v[56:59], v[160:163], v[184:187], v[56:59]
	v_mfma_f32_16x16x32_bf16 v[44:47], v[144:147], v[192:195], v[44:47]
	v_mfma_f32_16x16x32_bf16 v[40:43], v[160:163], v[192:195], v[40:43]
	v_mfma_f32_16x16x32_bf16 v[28:31], v[144:147], v[200:203], v[28:31]
	v_mfma_f32_16x16x32_bf16 v[24:27], v[160:163], v[200:203], v[24:27]
	v_mfma_f32_16x16x32_bf16 v[12:15], v[144:147], v[208:211], v[12:15]
	v_mfma_f32_16x16x32_bf16 v[8:11], v[160:163], v[208:211], v[8:11]
	s_setprio 0
	s_setprio 1
	v_mfma_f32_16x16x32_bf16 v[52:55], v[164:167], v[180:183], v[52:55]
	v_mfma_f32_16x16x32_bf16 v[48:51], v[172:175], v[180:183], v[48:51]
	v_mfma_f32_16x16x32_bf16 v[36:39], v[164:167], v[188:191], v[36:39]
	v_mfma_f32_16x16x32_bf16 v[32:35], v[172:175], v[188:191], v[32:35]
	v_mfma_f32_16x16x32_bf16 v[20:23], v[164:167], v[196:199], v[20:23]
	v_mfma_f32_16x16x32_bf16 v[16:19], v[172:175], v[196:199], v[16:19]
	v_mfma_f32_16x16x32_bf16 v[4:7], v[164:167], v[204:207], v[4:7]
	v_mfma_f32_16x16x32_bf16 v[0:3], v[172:175], v[204:207], v[0:3]
	s_add_i32 m0, s38, 0x2000
	s_nop 0
	global_load_lds_dwordx4 v[228:229], off
	v_mfma_f32_16x16x32_bf16 v[52:55], v[168:171], v[184:187], v[52:55]
	v_mfma_f32_16x16x32_bf16 v[48:51], v[176:179], v[184:187], v[48:51]
	v_mfma_f32_16x16x32_bf16 v[36:39], v[168:171], v[192:195], v[36:39]
	v_mfma_f32_16x16x32_bf16 v[32:35], v[176:179], v[192:195], v[32:35]
	v_mfma_f32_16x16x32_bf16 v[20:23], v[168:171], v[200:203], v[20:23]
	v_mfma_f32_16x16x32_bf16 v[16:19], v[176:179], v[200:203], v[16:19]
	v_mfma_f32_16x16x32_bf16 v[4:7], v[168:171], v[208:211], v[4:7]
	v_mfma_f32_16x16x32_bf16 v[0:3], v[176:179], v[208:211], v[0:3]
	s_setprio 0
	s_waitcnt vmcnt(4)
	s_barrier
	s_add_i32 s74, s74, 2
	s_add_u32 s0, s0, 0x100
	s_addc_u32 s1, s1, 0
	s_add_u32 s72, s72, 0x100
	s_addc_u32 s73, s73, 0
	s_cmp_gt_u32 s74, 29
	s_cbranch_scc0 .LBB0_1955
	s_and_b64 vcc, exec, s[16:17]
	s_cbranch_vccz .LBB0_1958
	s_barrier
